# plus HGRN2 chunk loop: loop-top counted waits (which waited for the previous chunk's store acks) replaced by one wait before the loop
# baseline (speedup 1.0000x reference)
; #define LAS __attribute__((address_space(3)))
; __device__ __forceinline__ void hg_c2_unit(const Args& a, const float* Gp, LAS unsigned char* lds, int unit, int tid) {
;     ...
;         for (int kt = 0; kt < 8; ++kt) { const int ko = 16 * kt + 4 * lq;
;             auto dgv = [&](int gg) -> f32x4 { return *(const LAS f32x4*)(DGL + gg * 128 + ko); };
;             f32x4 sq = ta[kt];
;             if (q >= 2) { const f32x4 w1 = dgv(4 * (q - 1)) * dgv(4 * (q - 1) + 1) * dgv(4 * (q - 1) + 2) * dgv(4 * (q - 1) + 3); sq = sq + w1 * tb[kt];
;                 if (q >= 3) { const f32x4 w2 = w1 * (dgv(4 * (q - 2)) * dgv(4 * (q - 2) + 1) * dgv(4 * (q - 2) + 2) * dgv(4 * (q - 2) + 3)); sq = sq + w2 * tc[kt]; } }
;             f32x4 e = {1.f, 1.f, 1.f, 1.f};
;             if (gi >= 1) e = e * dgv(4 * q); if (gi >= 2) e = e * dgv(4 * q + 1); if (gi >= 3) e = e * dgv(4 * q + 2);
;             S[kt] = e * sq + pg[kt]; }
;     }
;     _Float16 nlf[16]; bf16 nvv[16], nqq[16];
;     {   const size_t gofs = (size_t)(b * SEQ + g * 256 + seg * 16) * 512 + h * 128 + k;
;         const _Float16* lfp = (const _Float16*)(ws + WS_LF) + gofs; const bf16* vp = (const bf16*)(ws + WS_VV) + gofs; const bf16* qp = (const bf16*)(ws + WS_QS) + gofs;
; #pragma unroll
;         for (int i = 0; i < 16; ++i) { nlf[i] = lfp[(size_t)i * 512]; nvv[i] = vp[(size_t)i * 512]; nqq[i] = qp[(size_t)i * 512]; } }
.LBB0_918:
	s_lshl_b32 s34, s60, 6
	s_and_b32 s34, s34, 0xfffff000
	s_lshl_b32 s35, s91, 8
	s_or_b32 s34, s34, s35
	v_or_b32_e32 v2, s34, v185
	s_lshl_b32 s34, s90, 7
	v_ashrrev_i32_e32 v3, 31, v2
	s_and_b32 s34, s34, 0x180
	v_lshlrev_b64 v[6:7], 10, v[2:3]
	v_or_b32_e32 v2, s34, v136
	v_lshl_or_b32 v6, v2, 1, v6
	v_lshl_add_u64 v[114:115], s[68:69], 0, v[6:7]
	v_add_co_u32_e32 v112, vcc, s83, v114
	v_lshl_add_u64 v[134:135], s[70:71], 0, v[6:7]
	s_nop 0
	v_addc_co_u32_e32 v113, vcc, 0, v115, vcc
	v_add_co_u32_e32 v226, vcc, s84, v114
	v_lshl_add_u64 v[6:7], s[72:73], 0, v[6:7]
	s_nop 0
	v_addc_co_u32_e32 v227, vcc, 0, v115, vcc
	v_add_co_u32_e32 v124, vcc, s83, v134
	global_load_ushort v1, v[114:115], off
	global_load_ushort v3, v[134:135], off
	global_load_ushort v5, v[114:115], off offset:1024
	global_load_ushort v84, v[134:135], off offset:1024
	global_load_ushort v85, v[114:115], off offset:2048
	global_load_ushort v86, v[134:135], off offset:2048
	global_load_ushort v87, v[134:135], off offset:3072
	global_load_ushort v92, v[114:115], off offset:3072
	v_addc_co_u32_e32 v125, vcc, 0, v135, vcc
	v_add_co_u32_e32 v222, vcc, s84, v134
	global_load_ushort v93, v[6:7], off
	global_load_ushort v94, v[6:7], off offset:1024
	global_load_ushort v95, v[6:7], off offset:2048
	global_load_ushort v100, v[6:7], off offset:3072
	global_load_ushort v101, v[112:113], off offset:1024
	global_load_ushort v102, v[124:125], off offset:1024
	global_load_ushort v103, v[112:113], off offset:2048
	s_nop 0
	global_load_ushort v112, v[112:113], off offset:3072
	v_addc_co_u32_e32 v223, vcc, 0, v135, vcc
	v_add_co_u32_e32 v120, vcc, s83, v6
	s_and_b32 s35, s80, 0xfffff000
	s_nop 0
	v_addc_co_u32_e32 v121, vcc, 0, v7, vcc
	v_add_co_u32_e32 v132, vcc, s84, v6
	s_and_b32 s36, s89, 15
	s_nop 0
	v_addc_co_u32_e32 v133, vcc, 0, v7, vcc
	v_add_co_u32_e32 v218, vcc, s85, v114
	s_lshl_b32 s36, s36, 8
	s_nop 0
	v_addc_co_u32_e32 v219, vcc, 0, v115, vcc
	v_add_co_u32_e32 v220, vcc, s85, v134
	global_load_ushort v113, v[120:121], off offset:1024
	global_load_ushort v114, v[124:125], off offset:2048
	global_load_ushort v115, v[120:121], off offset:2048
	s_nop 0
	global_load_ushort v120, v[120:121], off offset:3072
	s_nop 0
	global_load_ushort v121, v[218:219], off
	global_load_ushort v122, v[218:219], off offset:1024
	global_load_ushort v123, v[218:219], off offset:2048
	s_nop 0
	global_load_ushort v124, v[124:125], off offset:3072
	s_nop 0
	global_load_ushort v125, v[132:133], off offset:-4096
	global_load_ushort v126, v[132:133], off
	global_load_ushort v127, v[222:223], off offset:1024
	global_load_ushort v128, v[132:133], off offset:1024
	global_load_ushort v129, v[222:223], off offset:2048
	global_load_ushort v130, v[132:133], off offset:2048
	global_load_ushort v131, v[132:133], off offset:3072
	s_nop 0
	global_load_ushort v132, v[222:223], off offset:3072
	v_addc_co_u32_e32 v221, vcc, 0, v135, vcc
	v_add_co_u32_e32 v6, vcc, s85, v6
	s_waitcnt lgkmcnt(0)
	v_pk_fma_f32 v[56:57], v[56:57], v[88:89], v[60:61]
	v_addc_co_u32_e32 v7, vcc, 0, v7, vcc
	global_load_ushort v133, v[220:221], off
	global_load_ushort v134, v[6:7], off
	global_load_ushort v135, v[220:221], off offset:1024
	global_load_ushort v214, v[6:7], off offset:1024
	global_load_ushort v215, v[220:221], off offset:2048
	global_load_ushort v216, v[6:7], off offset:2048
	global_load_ushort v217, v[220:221], off offset:3072
	s_nop 0
	global_load_ushort v218, v[218:219], off offset:3072
	s_nop 0
	global_load_ushort v219, v[226:227], off offset:-4096
	global_load_ushort v220, v[222:223], off offset:-4096
	global_load_ushort v221, v[226:227], off
	s_nop 0
	global_load_ushort v222, v[222:223], off
	s_nop 0
	global_load_ushort v223, v[226:227], off offset:1024
	global_load_ushort v224, v[226:227], off offset:2048
	global_load_ushort v225, v[226:227], off offset:3072
	s_nop 0
	global_load_ushort v226, v[6:7], off offset:3072
	v_or_b32_e32 v6, s35, v189
	v_or_b32_e32 v88, s36, v6
	v_or_b32_e32 v6, s35, v199
	s_lshl_b32 s66, s34, 1
	v_pk_fma_f32 v[58:59], v[58:59], v[90:91], v[62:63]
	v_pk_fma_f32 v[50:51], v[50:51], v[98:99], v[54:55]
	v_pk_fma_f32 v[48:49], v[48:49], v[96:97], v[52:53]
	v_pk_fma_f32 v[42:43], v[42:43], v[106:107], v[46:47]
	v_pk_fma_f32 v[40:41], v[40:41], v[104:105], v[44:45]
	v_pk_fma_f32 v[34:35], v[34:35], v[118:119], v[38:39]
	v_pk_fma_f32 v[32:33], v[32:33], v[116:117], v[36:37]
	v_pk_fma_f32 v[26:27], v[26:27], v[110:111], v[30:31]
	v_pk_fma_f32 v[24:25], v[24:25], v[108:109], v[28:29]
	v_pk_fma_f32 v[18:19], v[18:19], v[82:83], v[22:23]
	v_pk_fma_f32 v[16:17], v[16:17], v[80:81], v[20:21]
	v_pk_fma_f32 v[10:11], v[10:11], v[74:75], v[14:15]
	v_pk_fma_f32 v[8:9], v[8:9], v[72:73], v[12:13]
	v_or_b32_e32 v89, s36, v6
	v_pk_fma_f32 v[14:15], v[66:67], v[78:79], v[70:71]
	v_pk_fma_f32 v[12:13], v[64:65], v[76:77], v[68:69]
	s_mov_b32 s36, 0
	v_lshl_add_u64 v[6:7], v[142:143], 0, s[66:67]
	v_lshl_add_u64 v[72:73], v[144:145], 0, s[66:67]
	s_waitcnt vmcnt(0)
	s_branch .LBB0_920

; #define LAS __attribute__((address_space(3)))
; __device__ __forceinline__ unsigned pk2(float lo, float hi) { return pg8::cvt_pk_bf16(lo, hi); }
; __device__ __forceinline__ float bf2f(unsigned short u) { return __uint_as_float((unsigned)u << 16); }
; #define LBAR() do { asm volatile("s_waitcnt lgkmcnt(0)" ::: "memory"); __builtin_amdgcn_s_barrier(); asm volatile("" ::: "memory"); } while (0)
; __device__ __forceinline__ void hg_c2_unit(const Args& a, const float* Gp, LAS unsigned char* lds, int unit, int tid) {
;     ...
;         for (int i = 0; i < 16; ++i) { lf[i] = (float)nlf[i]; vv[i] = nvv[i]; qq[i] = nqq[i]; }
; #pragma unroll
;         for (int kt = 0; kt < 8; ++kt) { v2u w; w.x = pk2(S[kt][0], S[kt][1]); w.y = pk2(S[kt][2], S[kt][3]); *(LAS v2u*)(SL + (16 * wave + l15) * 136 + 16 * kt + 4 * lq) = w; }
;         float run = 0.f;
; #pragma unroll
;         for (int i = 0; i < 16; ++i) { run += lf[i]; bc[i] = run; }
;         segsum[seg * 128 + k] = run;
;         {   unsigned vq[8];
; #pragma unroll
;             for (int i = 0; i < 8; ++i) vq[i] = (unsigned)vv[2 * i] | ((unsigned)vv[2 * i + 1] << 16);
;             *(LAS v4u*)(Vt + k * 72 + seg * 16) = (v4u){vq[0], vq[1], vq[2], vq[3]}; *(LAS v4u*)(Vt + k * 72 + seg * 16 + 8) = (v4u){vq[4], vq[5], vq[6], vq[7]}; }
;         LBAR();
;         const float s0 = segsum[k], s1 = segsum[128 + k], s2 = segsum[256 + k], s3 = segsum[384 + k];
;         const float pre = (seg > 0 ? s0 : 0.f) + (seg > 1 ? s1 : 0.f) + (seg > 2 ? s2 : 0.f);
;         const float br = s0 + s1, blast = (s0 + s1) + (s2 + s3);
;         unsigned kp[8];
;         const float Ebr = __expf(br), Ebl = __expf(blast - br);
; #pragma unroll
;         for (int i = 0; i < 16; ++i) { const int s = seg * 16 + i; const float bb = pre + bc[i]; const float q = bf2f(qq[i]); const float kk = 1.f - __expf(lf[i]);
;             const float e1 = __expf(fminf(fmaxf(bb - br, -80.f), 80.f)), e3 = __builtin_amdgcn_rcpf(e1), e2 = e1 * Ebr, e4 = e3 * Ebl;
;             const unsigned w1 = pk2(q * e1, q * e2), w3 = pk2(kk * e3, kk * e4);
;             QT[s * 136 + k] = (bf16)(w1 & 0xffffu); Q2[s * 136 + k] = (bf16)(w1 >> 16); KT[s * 136 + k] = (bf16)(w3 & 0xffffu);
;             if (i & 1) kp[i >> 1] |= (w3 & 0xffff0000u); else kp[i >> 1] = w3 >> 16; }
.LBB0_920:
	v_cvt_f32_f16_e32 v39, v1
	v_cvt_pk_bf16_f32 v44, v8, v9
	v_cvt_pk_bf16_f32 v45, v10, v11
	v_cvt_pk_bf16_f32 v46, v16, v17
	v_cvt_pk_bf16_f32 v47, v18, v19
	v_cvt_f32_f16_e32 v52, v5
	ds_write2_b64 v200, v[44:45], v[46:47] offset1:4
	v_cvt_pk_bf16_f32 v44, v24, v25
	v_cvt_pk_bf16_f32 v45, v26, v27
	v_cvt_pk_bf16_f32 v46, v32, v33
	v_cvt_pk_bf16_f32 v47, v34, v35
	v_cvt_f32_f16_e32 v53, v85
	ds_write2_b64 v200, v[44:45], v[46:47] offset0:8 offset1:12
	v_cvt_pk_bf16_f32 v44, v40, v41
	v_cvt_pk_bf16_f32 v45, v42, v43
	v_cvt_pk_bf16_f32 v46, v48, v49
	v_cvt_pk_bf16_f32 v47, v50, v51
	v_cvt_f32_f16_e32 v54, v92
	ds_write2_b64 v200, v[44:45], v[46:47] offset0:16 offset1:20
	v_cvt_pk_bf16_f32 v44, v56, v57
	v_cvt_pk_bf16_f32 v45, v58, v59
	v_cvt_pk_bf16_f32 v46, v12, v13
	v_cvt_pk_bf16_f32 v47, v14, v15
	v_cvt_f32_f16_e32 v55, v219
	ds_write2_b64 v200, v[44:45], v[46:47] offset0:24 offset1:28
	v_add_f32_e32 v44, 0, v39
	v_cvt_f32_f16_e32 v60, v101
	v_add_f32_e32 v45, v44, v52
	v_cvt_f32_f16_e32 v61, v103
	v_add_f32_e32 v47, v45, v53
	v_cvt_f32_f16_e32 v62, v112
	v_add_f32_e32 v68, v47, v54
	v_cvt_f32_f16_e32 v63, v221
	v_add_f32_e32 v69, v68, v55
	v_cvt_f32_f16_e32 v64, v223
	v_add_f32_e32 v70, v69, v60
	v_cvt_f32_f16_e32 v65, v224
	v_add_f32_e32 v71, v70, v61
	v_cvt_f32_f16_e32 v66, v225
	v_add_f32_e32 v74, v71, v62
	v_cvt_f32_f16_e32 v67, v121
	v_add_f32_e32 v75, v74, v63
	v_cvt_f32_f16_e32 v38, v122
	v_add_f32_e32 v76, v75, v64
	v_cvt_f32_f16_e32 v37, v123
	v_add_f32_e32 v77, v76, v65
	v_cvt_f32_f16_e32 v36, v218
	v_add_f32_e32 v78, v77, v66
	v_add_f32_e32 v79, v78, v67
	v_add_f32_e32 v80, v79, v38
	v_add_f32_e32 v81, v80, v37
	v_lshlrev_b32_e32 v20, 16, v84
	v_lshlrev_b32_e32 v21, 16, v87
	v_lshlrev_b32_e32 v22, 16, v102
	v_lshlrev_b32_e32 v23, 16, v124
	v_lshlrev_b32_e32 v28, 16, v127
	v_lshlrev_b32_e32 v29, 16, v132
	v_lshlrev_b32_e32 v30, 16, v135
	v_lshlrev_b32_e32 v31, 16, v217
	v_add_f32_e32 v82, v81, v36
	v_or_b32_sdwa v20, v20, v3 dst_sel:DWORD dst_unused:UNUSED_PAD src0_sel:DWORD src1_sel:WORD_0
	v_or_b32_sdwa v21, v21, v86 dst_sel:DWORD dst_unused:UNUSED_PAD src0_sel:DWORD src1_sel:WORD_0
	v_or_b32_sdwa v22, v22, v220 dst_sel:DWORD dst_unused:UNUSED_PAD src0_sel:DWORD src1_sel:WORD_0
	v_or_b32_sdwa v23, v23, v114 dst_sel:DWORD dst_unused:UNUSED_PAD src0_sel:DWORD src1_sel:WORD_0
	v_or_b32_sdwa v28, v28, v222 dst_sel:DWORD dst_unused:UNUSED_PAD src0_sel:DWORD src1_sel:WORD_0
	v_or_b32_sdwa v29, v29, v129 dst_sel:DWORD dst_unused:UNUSED_PAD src0_sel:DWORD src1_sel:WORD_0
	v_or_b32_sdwa v30, v30, v133 dst_sel:DWORD dst_unused:UNUSED_PAD src0_sel:DWORD src1_sel:WORD_0
	v_or_b32_sdwa v31, v31, v215 dst_sel:DWORD dst_unused:UNUSED_PAD src0_sel:DWORD src1_sel:WORD_0
	ds_write_b32 v186, v82 offset:512
	ds_write_b128 v187, v[20:23] offset:56320
	ds_write_b128 v187, v[28:31] offset:56336
	s_waitcnt lgkmcnt(0)
	s_barrier
	ds_read2st64_b32 v[20:21], v211 offset0:2 offset1:4
	ds_read2st64_b32 v[22:23], v211 offset0:6 offset1:8
	s_waitcnt lgkmcnt(1)
	v_cndmask_b32_e64 v28, v20, 0, s[4:5]
	v_cndmask_b32_e64 v29, 0, v21, s[6:7]
	v_add_f32_e32 v28, v28, v29
	s_waitcnt lgkmcnt(0)
	v_cndmask_b32_e64 v29, 0, v22, s[8:9]
	v_add_f32_e32 v83, v28, v29
	v_mov_b32_e32 v28, v20
	v_mov_b32_e32 v29, v22
	v_mov_b32_e32 v22, v21
	v_pk_add_f32 v[30:31], v[28:29], v[22:23]
	v_mul_f32_e32 v22, 0x3fb8aa3b, v39
	v_pk_add_f32 v[28:29], v[30:31], v[30:31] op_sel:[0,1] op_sel_hi:[1,0]
	v_mul_f32_e32 v20, 0x3fb8aa3b, v30
	v_exp_f32_e32 v29, v20
	v_sub_f32_e32 v20, v28, v30
	v_mul_f32_e32 v21, 0x3fb8aa3b, v20
	v_add_f32_e32 v20, v44, v83
	v_sub_f32_e32 v20, v20, v30
	v_med3_f32 v20, v20, s86, v212
	v_mul_f32_e32 v20, 0x3fb8aa3b, v20
	v_exp_f32_e32 v20, v20
	v_exp_f32_e32 v23, v22
	v_exp_f32_e32 v90, v21
	v_lshlrev_b32_e32 v44, 16, v93
	v_rcp_f32_e32 v22, v20
	v_mul_f32_e32 v21, v29, v20
	v_sub_f32_e32 v46, 1.0, v23
	v_pk_mul_f32 v[20:21], v[20:21], v[44:45] op_sel_hi:[1,0]
	v_mul_f32_e32 v23, v90, v22
	v_cvt_pk_bf16_f32 v31, v20, v21
	v_pk_mul_f32 v[20:21], v[46:47], v[22:23] op_sel_hi:[0,1]
	v_cvt_pk_bf16_f32 v21, v20, v21
	v_add_f32_e32 v20, v45, v83
	v_sub_f32_e32 v20, v20, v30
	v_med3_f32 v20, v20, s86, v212
	v_mul_f32_e32 v20, 0x3fb8aa3b, v20
	v_exp_f32_e32 v20, v20
	v_mul_f32_e32 v22, 0x3fb8aa3b, v52
	v_exp_f32_e32 v23, v22
	ds_write_b16 v195, v31 offset:4096
	ds_write_b16_d16_hi v195, v31 offset:21504
	ds_write_b16 v195, v21 offset:38912
	v_rcp_f32_e32 v22, v20
	v_lshrrev_b32_e32 v31, 16, v21
	v_lshlrev_b32_e32 v44, 16, v94
	v_mul_f32_e32 v21, v29, v20
	v_sub_f32_e32 v46, 1.0, v23
	v_mul_f32_e32 v23, v90, v22
	v_pk_mul_f32 v[20:21], v[20:21], v[44:45] op_sel_hi:[1,0]
	s_nop 0
	v_cvt_pk_bf16_f32 v39, v20, v21
	v_pk_mul_f32 v[20:21], v[46:47], v[22:23] op_sel_hi:[0,1]
	v_cvt_pk_bf16_f32 v20, v20, v21
	v_add_f32_e32 v21, v47, v83
	v_sub_f32_e32 v21, v21, v30
	v_med3_f32 v21, v21, s86, v212
	v_mul_f32_e32 v21, 0x3fb8aa3b, v21
	v_exp_f32_e32 v22, v21
	v_mul_f32_e32 v21, 0x3fb8aa3b, v53
	v_exp_f32_e32 v21, v21
	v_lshlrev_b32_e32 v46, 16, v95
	v_rcp_f32_e32 v44, v22
	v_mul_f32_e32 v23, v29, v22
	v_sub_f32_e32 v52, 1.0, v21
	v_pk_mul_f32 v[22:23], v[22:23], v[46:47] op_sel_hi:[1,0]
	v_mul_f32_e32 v45, v90, v44
	v_cvt_pk_bf16_f32 v21, v22, v23
	v_pk_mul_f32 v[22:23], v[52:53], v[44:45] op_sel_hi:[0,1]
	ds_write_b16 v195, v39 offset:4368
	ds_write_b16_d16_hi v195, v39 offset:21776
	ds_write_b16 v195, v20 offset:39184
	v_cvt_pk_bf16_f32 v23, v22, v23
	ds_write_b16 v195, v21 offset:4640
	ds_write_b16_d16_hi v195, v21 offset:22048
	ds_write_b16 v195, v23 offset:39456
	v_add_f32_e32 v21, v68, v83
	v_sub_f32_e32 v21, v21, v30
	v_med3_f32 v21, v21, s86, v212
; __device__ __forceinline__ unsigned pk2(float lo, float hi) { return pg8::cvt_pk_bf16(lo, hi); }
; __device__ __forceinline__ float bf2f(unsigned short u) { return __uint_as_float((unsigned)u << 16); }
; __device__ __forceinline__ void hg_c2_unit(const Args& a, const float* Gp, LAS unsigned char* lds, int unit, int tid) {
;     ...
;         for (int i = 0; i < 16; ++i) { const int s = seg * 16 + i; const float bb = pre + bc[i]; const float q = bf2f(qq[i]); const float kk = 1.f - __expf(lf[i]);
;             const float e1 = __expf(fminf(fmaxf(bb - br, -80.f), 80.f)), e3 = __builtin_amdgcn_rcpf(e1), e2 = e1 * Ebr, e4 = e3 * Ebl;
;             const unsigned w1 = pk2(q * e1, q * e2), w3 = pk2(kk * e3, kk * e4);
;             QT[s * 136 + k] = (bf16)(w1 & 0xffffu); Q2[s * 136 + k] = (bf16)(w1 >> 16); KT[s * 136 + k] = (bf16)(w3 & 0xffffu);
;             if (i & 1) kp[i >> 1] |= (w3 & 0xffff0000u); else kp[i >> 1] = w3 >> 16; }
	v_mul_f32_e32 v21, 0x3fb8aa3b, v21
	v_exp_f32_e32 v22, v21
	v_mul_f32_e32 v21, 0x3fb8aa3b, v54
	v_exp_f32_e32 v21, v21
	v_and_or_b32 v20, v20, s87, v31
	v_rcp_f32_e32 v44, v22
	v_lshrrev_b32_e32 v31, 16, v23
	v_lshlrev_b32_e32 v46, 16, v100
	v_mul_f32_e32 v23, v29, v22
	v_sub_f32_e32 v52, 1.0, v21
	v_mul_f32_e32 v45, v90, v44
	v_pk_mul_f32 v[22:23], v[22:23], v[46:47] op_sel_hi:[1,0]
	v_lshlrev_b32_e32 v46, 16, v125
	v_cvt_pk_bf16_f32 v21, v22, v23
	v_pk_mul_f32 v[22:23], v[52:53], v[44:45] op_sel_hi:[0,1]
	v_cvt_pk_bf16_f32 v23, v22, v23
	ds_write_b16 v195, v21 offset:4912
	ds_write_b16_d16_hi v195, v21 offset:22320
	ds_write_b16 v195, v23 offset:39728
	v_add_f32_e32 v21, v69, v83
	v_sub_f32_e32 v21, v21, v30
	v_med3_f32 v21, v21, s86, v212
	v_mul_f32_e32 v21, 0x3fb8aa3b, v21
	v_exp_f32_e32 v22, v21
	v_mul_f32_e32 v21, 0x3fb8aa3b, v55
	v_exp_f32_e32 v39, v21
	v_and_or_b32 v21, v23, s87, v31
	v_rcp_f32_e32 v44, v22
	v_mul_f32_e32 v23, v29, v22
	v_sub_f32_e32 v52, 1.0, v39
	v_pk_mul_f32 v[22:23], v[22:23], v[46:47] op_sel_hi:[1,0]
	v_mul_f32_e32 v45, v90, v44
	v_cvt_pk_bf16_f32 v31, v22, v23
	v_pk_mul_f32 v[22:23], v[52:53], v[44:45] op_sel_hi:[0,1]
	v_cvt_pk_bf16_f32 v23, v22, v23
	v_add_f32_e32 v22, v70, v83
	v_sub_f32_e32 v22, v22, v30
	v_med3_f32 v22, v22, s86, v212
	v_mul_f32_e32 v22, 0x3fb8aa3b, v22
	v_exp_f32_e32 v22, v22
	ds_write_b16 v195, v31 offset:5184
	ds_write_b16_d16_hi v195, v31 offset:22592
	ds_write_b16 v195, v23 offset:40000
	v_mul_f32_e32 v31, 0x3fb8aa3b, v60
	v_exp_f32_e32 v31, v31
	v_rcp_f32_e32 v44, v22
	v_lshrrev_b32_e32 v39, 16, v23
	v_lshlrev_b32_e32 v46, 16, v113
	v_mul_f32_e32 v23, v29, v22
	v_sub_f32_e32 v52, 1.0, v31
	v_mul_f32_e32 v45, v90, v44
	v_pk_mul_f32 v[22:23], v[22:23], v[46:47] op_sel_hi:[1,0]
	s_nop 0
	v_cvt_pk_bf16_f32 v31, v22, v23
	v_pk_mul_f32 v[22:23], v[52:53], v[44:45] op_sel_hi:[0,1]
	v_cvt_pk_bf16_f32 v22, v22, v23
	v_add_f32_e32 v23, v71, v83
	v_sub_f32_e32 v23, v23, v30
	v_med3_f32 v23, v23, s86, v212
	v_mul_f32_e32 v23, 0x3fb8aa3b, v23
	v_exp_f32_e32 v44, v23
	v_mul_f32_e32 v23, 0x3fb8aa3b, v61
	v_exp_f32_e32 v23, v23
	v_lshlrev_b32_e32 v52, 16, v115
	v_rcp_f32_e32 v46, v44
	v_mul_f32_e32 v45, v29, v44
	v_sub_f32_e32 v54, 1.0, v23
	v_pk_mul_f32 v[44:45], v[44:45], v[52:53] op_sel_hi:[1,0]
	v_mul_f32_e32 v47, v90, v46
	v_cvt_pk_bf16_f32 v23, v44, v45
	v_pk_mul_f32 v[44:45], v[54:55], v[46:47] op_sel_hi:[0,1]
	ds_write_b16 v195, v31 offset:5456
	ds_write_b16_d16_hi v195, v31 offset:22864
	ds_write_b16 v195, v22 offset:40272
	v_cvt_pk_bf16_f32 v31, v44, v45
	ds_write_b16 v195, v23 offset:5728
	ds_write_b16_d16_hi v195, v23 offset:23136
	ds_write_b16 v195, v31 offset:40544
	v_add_f32_e32 v23, v74, v83
	v_sub_f32_e32 v23, v23, v30
	v_med3_f32 v23, v23, s86, v212
	v_mul_f32_e32 v23, 0x3fb8aa3b, v23
	v_exp_f32_e32 v44, v23
	v_mul_f32_e32 v23, 0x3fb8aa3b, v62
	v_exp_f32_e32 v23, v23
	v_lshlrev_b32_e32 v52, 16, v120
	v_rcp_f32_e32 v46, v44
	v_mul_f32_e32 v45, v29, v44
	v_sub_f32_e32 v54, 1.0, v23
	v_pk_mul_f32 v[44:45], v[44:45], v[52:53] op_sel_hi:[1,0]
	v_mul_f32_e32 v47, v90, v46
	v_cvt_pk_bf16_f32 v23, v44, v45
	v_pk_mul_f32 v[44:45], v[54:55], v[46:47] op_sel_hi:[0,1]
	v_and_or_b32 v22, v22, s87, v39
	v_cvt_pk_bf16_f32 v39, v44, v45
	ds_write_b16 v195, v23 offset:6000
	ds_write_b16_d16_hi v195, v23 offset:23408
	ds_write_b16 v195, v39 offset:40816
	v_add_f32_e32 v23, v75, v83
	v_sub_f32_e32 v23, v23, v30
	v_med3_f32 v23, v23, s86, v212
	v_mul_f32_e32 v23, 0x3fb8aa3b, v23
	v_exp_f32_e32 v44, v23
	v_mul_f32_e32 v23, 0x3fb8aa3b, v63
	v_exp_f32_e32 v45, v23
	v_lshlrev_b32_e32 v52, 16, v126
	v_rcp_f32_e32 v46, v44
	v_lshrrev_b32_e32 v31, 16, v31
	v_sub_f32_e32 v54, 1.0, v45
	v_mul_f32_e32 v45, v29, v44
	v_mul_f32_e32 v47, v90, v46
	v_pk_mul_f32 v[44:45], v[44:45], v[52:53] op_sel_hi:[1,0]
	v_and_or_b32 v23, v39, s87, v31
	v_cvt_pk_bf16_f32 v31, v44, v45
	v_pk_mul_f32 v[44:45], v[54:55], v[46:47] op_sel_hi:[0,1]
	v_cvt_pk_bf16_f32 v39, v44, v45
	ds_write_b16 v195, v31 offset:6272
	ds_write_b16_d16_hi v195, v31 offset:23680
	ds_write_b16 v195, v39 offset:41088
	v_add_f32_e32 v31, v76, v83
	v_sub_f32_e32 v31, v31, v30
	v_med3_f32 v31, v31, s86, v212
	v_mul_f32_e32 v31, 0x3fb8aa3b, v31
	v_exp_f32_e32 v44, v31
	v_mul_f32_e32 v31, 0x3fb8aa3b, v64
	v_exp_f32_e32 v31, v31
	v_lshlrev_b32_e32 v52, 16, v128
	v_rcp_f32_e32 v46, v44
	v_mul_f32_e32 v45, v29, v44
	v_sub_f32_e32 v54, 1.0, v31
	v_pk_mul_f32 v[44:45], v[44:45], v[52:53] op_sel_hi:[1,0]
	v_mul_f32_e32 v47, v90, v46
	v_cvt_pk_bf16_f32 v31, v44, v45
	v_pk_mul_f32 v[44:45], v[54:55], v[46:47] op_sel_hi:[0,1]
; #define LAS __attribute__((address_space(3)))
; __device__ __forceinline__ unsigned pk2(float lo, float hi) { return pg8::cvt_pk_bf16(lo, hi); }
; __device__ __forceinline__ float bf2f(unsigned short u) { return __uint_as_float((unsigned)u << 16); }
; __device__ __forceinline__ void hg_c2_unit(const Args& a, const float* Gp, LAS unsigned char* lds, int unit, int tid) {
;     ...
;         for (int i = 0; i < 16; ++i) { const int s = seg * 16 + i; const float bb = pre + bc[i]; const float q = bf2f(qq[i]); const float kk = 1.f - __expf(lf[i]);
;             const float e1 = __expf(fminf(fmaxf(bb - br, -80.f), 80.f)), e3 = __builtin_amdgcn_rcpf(e1), e2 = e1 * Ebr, e4 = e3 * Ebl;
;             const unsigned w1 = pk2(q * e1, q * e2), w3 = pk2(kk * e3, kk * e4);
;             QT[s * 136 + k] = (bf16)(w1 & 0xffffu); Q2[s * 136 + k] = (bf16)(w1 >> 16); KT[s * 136 + k] = (bf16)(w3 & 0xffffu);
;             if (i & 1) kp[i >> 1] |= (w3 & 0xffff0000u); else kp[i >> 1] = w3 >> 16; }
;         *(LAS v4u*)(KPt + k * 72 + seg * 16) = (v4u){kp[0], kp[1], kp[2], kp[3]}; *(LAS v4u*)(KPt + k * 72 + seg * 16 + 8) = (v4u){kp[4], kp[5], kp[6], kp[7]};
;         if (seg == 0) dl[k] = __expf(blast);
	v_cvt_pk_bf16_f32 v44, v44, v45
	ds_write_b16 v195, v31 offset:6544
	ds_write_b16_d16_hi v195, v31 offset:23952
	ds_write_b16 v195, v44 offset:41360
	v_add_f32_e32 v31, v77, v83
	v_sub_f32_e32 v31, v31, v30
	v_med3_f32 v31, v31, s86, v212
	v_mul_f32_e32 v31, 0x3fb8aa3b, v31
	v_exp_f32_e32 v46, v31
	v_mul_f32_e32 v31, 0x3fb8aa3b, v65
	v_exp_f32_e32 v31, v31
	v_lshlrev_b32_e32 v54, 16, v130
	v_rcp_f32_e32 v52, v46
	v_mul_f32_e32 v47, v29, v46
	v_sub_f32_e32 v60, 1.0, v31
	v_pk_mul_f32 v[46:47], v[46:47], v[54:55] op_sel_hi:[1,0]
	v_mul_f32_e32 v53, v90, v52
	v_lshrrev_b32_e32 v39, 16, v39
	v_cvt_pk_bf16_f32 v31, v46, v47
	v_pk_mul_f32 v[46:47], v[60:61], v[52:53] op_sel_hi:[0,1]
	v_and_or_b32 v44, v44, s87, v39
	v_cvt_pk_bf16_f32 v39, v46, v47
	ds_write_b16 v195, v31 offset:6816
	ds_write_b16_d16_hi v195, v31 offset:24224
	ds_write_b16 v195, v39 offset:41632
	v_add_f32_e32 v31, v78, v83
	v_sub_f32_e32 v31, v31, v30
	v_med3_f32 v31, v31, s86, v212
	v_mul_f32_e32 v31, 0x3fb8aa3b, v31
	v_exp_f32_e32 v46, v31
	v_mul_f32_e32 v31, 0x3fb8aa3b, v66
	v_exp_f32_e32 v31, v31
	v_lshlrev_b32_e32 v54, 16, v131
	v_rcp_f32_e32 v52, v46
	v_mul_f32_e32 v47, v29, v46
	v_sub_f32_e32 v60, 1.0, v31
	v_pk_mul_f32 v[46:47], v[46:47], v[54:55] op_sel_hi:[1,0]
	v_mul_f32_e32 v53, v90, v52
	v_cvt_pk_bf16_f32 v31, v46, v47
	v_pk_mul_f32 v[46:47], v[60:61], v[52:53] op_sel_hi:[0,1]
	v_cvt_pk_bf16_f32 v45, v46, v47
	ds_write_b16 v195, v31 offset:7088
	ds_write_b16_d16_hi v195, v31 offset:24496
	ds_write_b16 v195, v45 offset:41904
	v_add_f32_e32 v31, v79, v83
	v_sub_f32_e32 v31, v31, v30
	v_med3_f32 v31, v31, s86, v212
	v_mul_f32_e32 v31, 0x3fb8aa3b, v31
	v_exp_f32_e32 v46, v31
	v_mul_f32_e32 v31, 0x3fb8aa3b, v67
	v_exp_f32_e32 v31, v31
	v_lshlrev_b32_e32 v54, 16, v134
	v_rcp_f32_e32 v52, v46
	v_mul_f32_e32 v47, v29, v46
	v_sub_f32_e32 v60, 1.0, v31
	v_pk_mul_f32 v[46:47], v[46:47], v[54:55] op_sel_hi:[1,0]
	v_mul_f32_e32 v53, v90, v52
	v_lshrrev_b32_e32 v39, 16, v39
	v_cvt_pk_bf16_f32 v31, v46, v47
	v_pk_mul_f32 v[46:47], v[60:61], v[52:53] op_sel_hi:[0,1]
	v_and_or_b32 v45, v45, s87, v39
	v_cvt_pk_bf16_f32 v39, v46, v47
	ds_write_b16 v195, v31 offset:7360
	ds_write_b16_d16_hi v195, v31 offset:24768
	ds_write_b16 v195, v39 offset:42176
	v_add_f32_e32 v31, v80, v83
	v_sub_f32_e32 v31, v31, v30
	v_med3_f32 v31, v31, s86, v212
	v_mul_f32_e32 v31, 0x3fb8aa3b, v31
	v_exp_f32_e32 v46, v31
	v_mul_f32_e32 v31, 0x3fb8aa3b, v38
	v_exp_f32_e32 v31, v31
	v_lshrrev_b32_e32 v53, 16, v39
	v_rcp_f32_e32 v38, v46
	v_lshlrev_b32_e32 v52, 16, v214
	v_mul_f32_e32 v47, v29, v46
	v_sub_f32_e32 v54, 1.0, v31
	v_mul_f32_e32 v39, v90, v38
	v_pk_mul_f32 v[46:47], v[46:47], v[52:53] op_sel_hi:[1,0]
	v_pk_mul_f32 v[38:39], v[54:55], v[38:39] op_sel_hi:[0,1]
	v_cvt_pk_bf16_f32 v31, v46, v47
	v_cvt_pk_bf16_f32 v39, v38, v39
	ds_write_b16 v195, v31 offset:7632
	ds_write_b16_d16_hi v195, v31 offset:25040
	ds_write_b16 v195, v39 offset:42448
	v_add_f32_e32 v31, v81, v83
	v_sub_f32_e32 v31, v31, v30
	v_med3_f32 v31, v31, s86, v212
	v_mul_f32_e32 v31, 0x3fb8aa3b, v31
	v_exp_f32_e32 v38, v31
	v_mul_f32_e32 v31, 0x3fb8aa3b, v37
	v_exp_f32_e32 v31, v31
	v_and_or_b32 v46, v39, s87, v53
	v_rcp_f32_e32 v52, v38
	v_lshlrev_b32_e32 v54, 16, v216
	v_mul_f32_e32 v39, v29, v38
	v_sub_f32_e32 v60, 1.0, v31
	v_mul_f32_e32 v53, v90, v52
	v_pk_mul_f32 v[38:39], v[38:39], v[54:55] op_sel_hi:[1,0]
	s_nop 0
	v_cvt_pk_bf16_f32 v31, v38, v39
	v_pk_mul_f32 v[38:39], v[60:61], v[52:53] op_sel_hi:[0,1]
	v_cvt_pk_bf16_f32 v37, v38, v39
	ds_write_b16 v195, v31 offset:7904
	ds_write_b16_d16_hi v195, v31 offset:25312
	ds_write_b16 v195, v37 offset:42720
	v_add_f32_e32 v31, v82, v83
	v_sub_f32_e32 v30, v31, v30
	v_med3_f32 v30, v30, s86, v212
	v_mul_f32_e32 v30, 0x3fb8aa3b, v30
	v_exp_f32_e32 v30, v30
	v_mul_f32_e32 v31, 0x3fb8aa3b, v36
	v_exp_f32_e32 v31, v31
	v_lshrrev_b32_e32 v39, 16, v37
	v_rcp_f32_e32 v36, v30
	s_waitcnt vmcnt(0)
	v_lshlrev_b32_e32 v38, 16, v226
	v_sub_f32_e32 v52, 1.0, v31
	v_mul_f32_e32 v31, v29, v30
	v_mul_f32_e32 v37, v90, v36
	v_pk_mul_f32 v[30:31], v[30:31], v[38:39] op_sel_hi:[1,0]
	s_nop 0
	v_cvt_pk_bf16_f32 v29, v30, v31
	v_pk_mul_f32 v[30:31], v[52:53], v[36:37] op_sel_hi:[0,1]
	v_cvt_pk_bf16_f32 v30, v30, v31
	ds_write_b16 v196, v29 offset:4096
	ds_write_b16_d16_hi v196, v29 offset:21504
	ds_write_b16 v196, v30 offset:38912
	v_and_or_b32 v47, v30, s87, v39
	ds_write_b128 v188, v[20:23]
	ds_write_b128 v188, v[44:47] offset:16
	s_and_saveexec_b64 s[34:35], s[4:5]
	s_cbranch_execz .LBB0_922
	v_mul_f32_e32 v20, 0x3fb8aa3b, v28
	v_exp_f32_e32 v20, v20
	ds_write_b32 v211, v20
